# cmp_mlp_block l-loop rewritten by hand: rolling one-l-ahead prefetch of W1 fragments and pos rows, counted vmcnt(21) per step
# speedup vs baseline: 1.0085x; 1.0005x over previous
; #define MFMA32(a, b, c) __builtin_amdgcn_mfma_f32_32x32x16_bf16((a), (b), (c), 0, 0, 0)
; DI float bflo(unsigned w) { return __uint_as_float(w << 16); }
; DI float bfhi(unsigned w) { return __uint_as_float(w & 0xffff0000u); }
; DI float gelu_tanh(float x) {
;   const float y = 0.7978845608028654f * (x + 0.044715f * x * x * x);
;   return 0.5f * x * (1.f + tanhf(y));
; }
; DI void cmp_mlp_block(const Params& p, int layer, int item, int wid, int lane) {
;     ...
;   const u16* wfr = w1t + (size_t)wid * 256 * 64 * 8 + lane * 8;
; #pragma unroll 2
;   for (int l = 0; l < 32; ++l) {
;     bf16x8 wf[8];
; #pragma unroll
;     for (int s2 = 0; s2 < 8; ++s2) wf[s2] = ldg8(wfr + (size_t)(l * 8 + s2) * 64 * 8);
;     const char* drow = smem + ((l & 15) * 33 + (l >> 4) + u) * 272 + 16 * h;
;     const float* prow = pos + l * 128 + 8 * h;
; #pragma unroll
;     for (int s2 = 0; s2 < 8; ++s2) {
;       const uint4 dv = *reinterpret_cast<const uint4*>(drow + 32 * s2);
;       const float4 p0 = *reinterpret_cast<const float4*>(prow + 16 * s2), p1 = *reinterpret_cast<const float4*>(prow + 16 * s2 + 4);
;       typedef __attribute__((ext_vector_type(4))) unsigned u32x4;
;       u32x4 w;
;       w[0] = pk2(bflo(dv.x) + p0.x, bfhi(dv.x) + p0.y);
;       w[1] = pk2(bflo(dv.y) + p0.z, bfhi(dv.y) + p0.w);
;       w[2] = pk2(bflo(dv.z) + p1.x, bfhi(dv.z) + p1.y);
;       w[3] = pk2(bflo(dv.w) + p1.z, bfhi(dv.w) + p1.w);
;       const bf16x8 df = __builtin_bit_cast(bf16x8, w);
;       hacc = MFMA32(wf[s2], df, hacc);
;     }
;   }
.LBB0_303:
	s_or_b64 exec, exec, s[2:3]
	v_readlane_b32 s52, v254, 0
	s_and_b64 s[2:3], s[8:9], exec
	v_readlane_b32 s60, v254, 8
	v_readlane_b32 s62, v254, 10
	s_mov_b32 s2, 0x4300000
	v_readlane_b32 s61, v254, 9
	v_readlane_b32 s63, v254, 11
	s_cselect_b32 s10, s60, s62
	s_cselect_b32 s2, s2, 0x4500000
	s_cselect_b32 s11, s61, s63
	s_add_u32 s10, s10, s6
	s_mov_b32 s3, s28
	s_addc_u32 s11, s11, s7
	v_lshlrev_b32_e32 v0, 2, v52
	v_mov_b32_e32 v2, 0
	v_lshl_add_u64 v[68:69], s[10:11], 0, v[0:1]
	v_lshl_add_u64 v[70:71], v[64:65], 0, s[2:3]
	s_mov_b32 s2, 1
	s_mov_b64 s[10:11], 0
	v_mov_b32_e32 v3, v2
	v_mov_b32_e32 v4, v2
	v_mov_b32_e32 v5, v2
	v_mov_b32_e32 v6, v2
	v_mov_b32_e32 v7, v2
	v_mov_b32_e32 v8, v2
	v_mov_b32_e32 v9, v2
	v_mov_b32_e32 v10, v2
	v_mov_b32_e32 v11, v2
	v_mov_b32_e32 v12, v2
	v_mov_b32_e32 v13, v2
	v_mov_b32_e32 v14, v2
	v_mov_b32_e32 v15, v2
	v_mov_b32_e32 v16, v2
	v_mov_b32_e32 v17, v2
	v_readlane_b32 s53, v254, 1
	v_readlane_b32 s54, v254, 2
	v_readlane_b32 s55, v254, 3
	v_readlane_b32 s56, v254, 4
	v_readlane_b32 s57, v254, 5
	v_readlane_b32 s58, v254, 6
	v_readlane_b32 s59, v254, 7
	v_readlane_b32 s64, v254, 12
	v_readlane_b32 s65, v254, 13
	v_readlane_b32 s66, v254, 14
	v_readlane_b32 s67, v254, 15
	s_waitcnt lgkmcnt(0)
	s_barrier
	s_mov_b64 s[18:19], 0x2000
	v_add_co_u32_e32 v174, vcc, 0xffffc400, v70
	s_nop 1
	v_addc_co_u32_e32 v175, vcc, -1, v71, vcc
	v_add_co_u32_e32 v176, vcc, 0xffffd400, v70
	s_nop 1
	v_addc_co_u32_e32 v177, vcc, -1, v71, vcc
	v_mad_u32_u24 v75, v53, s38, v182
	v_lshl_add_u64 v[72:73], v[68:69], 0, s[10:11]
	s_mov_b32 s2, 0
	global_load_dwordx4 v[18:21], v[174:175], off
	global_load_dwordx4 v[106:109], v[72:73], off
	global_load_dwordx4 v[110:113], v[72:73], off offset:16
	global_load_dwordx4 v[22:25], v[174:175], off offset:1024
	global_load_dwordx4 v[114:117], v[72:73], off offset:64
	global_load_dwordx4 v[118:121], v[72:73], off offset:80
	global_load_dwordx4 v[26:29], v[174:175], off offset:2048
	global_load_dwordx4 v[122:125], v[72:73], off offset:128
	global_load_dwordx4 v[126:129], v[72:73], off offset:144
	global_load_dwordx4 v[30:33], v[174:175], off offset:3072
	global_load_dwordx4 v[130:133], v[72:73], off offset:192
	global_load_dwordx4 v[134:137], v[72:73], off offset:208
	global_load_dwordx4 v[34:37], v[176:177], off
	global_load_dwordx4 v[138:141], v[72:73], off offset:256
	global_load_dwordx4 v[142:145], v[72:73], off offset:272
	global_load_dwordx4 v[38:41], v[176:177], off offset:1024
	global_load_dwordx4 v[146:149], v[72:73], off offset:320
	global_load_dwordx4 v[150:153], v[72:73], off offset:336
	global_load_dwordx4 v[42:45], v[176:177], off offset:2048
	global_load_dwordx4 v[154:157], v[72:73], off offset:384
	global_load_dwordx4 v[158:161], v[72:73], off offset:400
	global_load_dwordx4 v[46:49], v[176:177], off offset:3072
	global_load_dwordx4 v[166:169], v[72:73], off offset:448
	global_load_dwordx4 v[170:173], v[72:73], off offset:464
	v_lshl_add_u64 v[174:175], v[174:175], 0, s[18:19]
	v_lshl_add_u64 v[176:177], v[176:177], 0, s[18:19]
	s_movk_i32 s10, 0x200
.Lcm_loop:
	s_and_b32 s3, s2, 15
	s_mul_i32 s3, s3, 33
	s_lshr_b32 s17, s2, 4
	s_add_i32 s3, s3, s17
	s_mul_i32 s3, s3, 0x110
	v_add_u32_e32 v74, s3, v75
	ds_read_b128 v[78:81], v74
	ds_read_b128 v[82:85], v74 offset:32
	ds_read_b128 v[86:89], v74 offset:64
	ds_read_b128 v[188:191], v74 offset:96
	ds_read_b128 v[192:195], v74 offset:128
	ds_read_b128 v[210:213], v74 offset:160
	ds_read_b128 v[214:217], v74 offset:192
	ds_read_b128 v[218:221], v74 offset:224
	v_lshl_add_u64 v[72:73], v[68:69], 0, s[10:11]
	s_waitcnt vmcnt(21) lgkmcnt(7)
	v_lshlrev_b32_e32 v90, 16, v78
	v_and_b32_e32 v91, 0xffff0000, v78
	v_lshlrev_b32_e32 v222, 16, v79
	v_and_b32_e32 v223, 0xffff0000, v79
	v_pk_add_f32 v[90:91], v[106:107], v[90:91]
	v_pk_add_f32 v[222:223], v[108:109], v[222:223]
	v_cvt_pk_bf16_f32 v92, v90, v91
	v_cvt_pk_bf16_f32 v93, v222, v223
	v_lshlrev_b32_e32 v90, 16, v80
	v_and_b32_e32 v91, 0xffff0000, v80
	v_lshlrev_b32_e32 v222, 16, v81
	v_and_b32_e32 v223, 0xffff0000, v81
	v_pk_add_f32 v[90:91], v[110:111], v[90:91]
	v_pk_add_f32 v[222:223], v[112:113], v[222:223]
	v_cvt_pk_bf16_f32 v94, v90, v91
	v_cvt_pk_bf16_f32 v95, v222, v223
	s_nop 1
	v_mfma_f32_32x32x16_bf16 v[2:17], v[18:21], v[92:95], v[2:17]
	global_load_dwordx4 v[18:21], v[174:175], off
	global_load_dwordx4 v[106:109], v[72:73], off
	global_load_dwordx4 v[110:113], v[72:73], off offset:16
	s_waitcnt vmcnt(21) lgkmcnt(6)
	v_lshlrev_b32_e32 v90, 16, v82
	v_and_b32_e32 v91, 0xffff0000, v82
	v_lshlrev_b32_e32 v222, 16, v83
	v_and_b32_e32 v223, 0xffff0000, v83
	v_pk_add_f32 v[90:91], v[114:115], v[90:91]
	v_pk_add_f32 v[222:223], v[116:117], v[222:223]
	v_cvt_pk_bf16_f32 v92, v90, v91
	v_cvt_pk_bf16_f32 v93, v222, v223
	v_lshlrev_b32_e32 v90, 16, v84
	v_and_b32_e32 v91, 0xffff0000, v84
	v_lshlrev_b32_e32 v222, 16, v85
	v_and_b32_e32 v223, 0xffff0000, v85
	v_pk_add_f32 v[90:91], v[118:119], v[90:91]
	v_pk_add_f32 v[222:223], v[120:121], v[222:223]
	v_cvt_pk_bf16_f32 v94, v90, v91
	v_cvt_pk_bf16_f32 v95, v222, v223
	s_nop 1
	v_mfma_f32_32x32x16_bf16 v[2:17], v[22:25], v[92:95], v[2:17]
	global_load_dwordx4 v[22:25], v[174:175], off offset:1024
	global_load_dwordx4 v[114:117], v[72:73], off offset:64
	global_load_dwordx4 v[118:121], v[72:73], off offset:80
	s_waitcnt vmcnt(21) lgkmcnt(5)
; #define MFMA32(a, b, c) __builtin_amdgcn_mfma_f32_32x32x16_bf16((a), (b), (c), 0, 0, 0)
; DI float bflo(unsigned w) { return __uint_as_float(w << 16); }
; DI float bfhi(unsigned w) { return __uint_as_float(w & 0xffff0000u); }
; DI void cmp_mlp_block(const Params& p, int layer, int item, int wid, int lane) {
;     ...
;   for (int l = 0; l < 32; ++l) {
;     bf16x8 wf[8];
; #pragma unroll
;     for (int s2 = 0; s2 < 8; ++s2) wf[s2] = ldg8(wfr + (size_t)(l * 8 + s2) * 64 * 8);
;     const char* drow = smem + ((l & 15) * 33 + (l >> 4) + u) * 272 + 16 * h;
;     const float* prow = pos + l * 128 + 8 * h;
; #pragma unroll
;     for (int s2 = 0; s2 < 8; ++s2) {
;       const uint4 dv = *reinterpret_cast<const uint4*>(drow + 32 * s2);
;       const float4 p0 = *reinterpret_cast<const float4*>(prow + 16 * s2), p1 = *reinterpret_cast<const float4*>(prow + 16 * s2 + 4);
;       typedef __attribute__((ext_vector_type(4))) unsigned u32x4;
;       u32x4 w;
;       w[0] = pk2(bflo(dv.x) + p0.x, bfhi(dv.x) + p0.y);
;       w[1] = pk2(bflo(dv.y) + p0.z, bfhi(dv.y) + p0.w);
;       w[2] = pk2(bflo(dv.z) + p1.x, bfhi(dv.z) + p1.y);
;       w[3] = pk2(bflo(dv.w) + p1.z, bfhi(dv.w) + p1.w);
;       const bf16x8 df = __builtin_bit_cast(bf16x8, w);
;       hacc = MFMA32(wf[s2], df, hacc);
;     }
;   }
	v_lshlrev_b32_e32 v90, 16, v86
	v_and_b32_e32 v91, 0xffff0000, v86
	v_lshlrev_b32_e32 v222, 16, v87
	v_and_b32_e32 v223, 0xffff0000, v87
	v_pk_add_f32 v[90:91], v[122:123], v[90:91]
	v_pk_add_f32 v[222:223], v[124:125], v[222:223]
	v_cvt_pk_bf16_f32 v92, v90, v91
	v_cvt_pk_bf16_f32 v93, v222, v223
	v_lshlrev_b32_e32 v90, 16, v88
	v_and_b32_e32 v91, 0xffff0000, v88
	v_lshlrev_b32_e32 v222, 16, v89
	v_and_b32_e32 v223, 0xffff0000, v89
	v_pk_add_f32 v[90:91], v[126:127], v[90:91]
	v_pk_add_f32 v[222:223], v[128:129], v[222:223]
	v_cvt_pk_bf16_f32 v94, v90, v91
	v_cvt_pk_bf16_f32 v95, v222, v223
	s_nop 1
	v_mfma_f32_32x32x16_bf16 v[2:17], v[26:29], v[92:95], v[2:17]
	global_load_dwordx4 v[26:29], v[174:175], off offset:2048
	global_load_dwordx4 v[122:125], v[72:73], off offset:128
	global_load_dwordx4 v[126:129], v[72:73], off offset:144
	s_waitcnt vmcnt(21) lgkmcnt(4)
	v_lshlrev_b32_e32 v90, 16, v188
	v_and_b32_e32 v91, 0xffff0000, v188
	v_lshlrev_b32_e32 v222, 16, v189
	v_and_b32_e32 v223, 0xffff0000, v189
	v_pk_add_f32 v[90:91], v[130:131], v[90:91]
	v_pk_add_f32 v[222:223], v[132:133], v[222:223]
	v_cvt_pk_bf16_f32 v92, v90, v91
	v_cvt_pk_bf16_f32 v93, v222, v223
	v_lshlrev_b32_e32 v90, 16, v190
	v_and_b32_e32 v91, 0xffff0000, v190
	v_lshlrev_b32_e32 v222, 16, v191
	v_and_b32_e32 v223, 0xffff0000, v191
	v_pk_add_f32 v[90:91], v[134:135], v[90:91]
	v_pk_add_f32 v[222:223], v[136:137], v[222:223]
	v_cvt_pk_bf16_f32 v94, v90, v91
	v_cvt_pk_bf16_f32 v95, v222, v223
	s_nop 1
	v_mfma_f32_32x32x16_bf16 v[2:17], v[30:33], v[92:95], v[2:17]
	global_load_dwordx4 v[30:33], v[174:175], off offset:3072
	global_load_dwordx4 v[130:133], v[72:73], off offset:192
	global_load_dwordx4 v[134:137], v[72:73], off offset:208
	s_waitcnt vmcnt(21) lgkmcnt(3)
	v_lshlrev_b32_e32 v90, 16, v192
	v_and_b32_e32 v91, 0xffff0000, v192
	v_lshlrev_b32_e32 v222, 16, v193
	v_and_b32_e32 v223, 0xffff0000, v193
	v_pk_add_f32 v[90:91], v[138:139], v[90:91]
	v_pk_add_f32 v[222:223], v[140:141], v[222:223]
	v_cvt_pk_bf16_f32 v92, v90, v91
	v_cvt_pk_bf16_f32 v93, v222, v223
	v_lshlrev_b32_e32 v90, 16, v194
	v_and_b32_e32 v91, 0xffff0000, v194
	v_lshlrev_b32_e32 v222, 16, v195
	v_and_b32_e32 v223, 0xffff0000, v195
	v_pk_add_f32 v[90:91], v[142:143], v[90:91]
	v_pk_add_f32 v[222:223], v[144:145], v[222:223]
	v_cvt_pk_bf16_f32 v94, v90, v91
	v_cvt_pk_bf16_f32 v95, v222, v223
	s_nop 1
	v_mfma_f32_32x32x16_bf16 v[2:17], v[34:37], v[92:95], v[2:17]
	global_load_dwordx4 v[34:37], v[176:177], off
	global_load_dwordx4 v[138:141], v[72:73], off offset:256
	global_load_dwordx4 v[142:145], v[72:73], off offset:272
	s_waitcnt vmcnt(21) lgkmcnt(2)
	v_lshlrev_b32_e32 v90, 16, v210
	v_and_b32_e32 v91, 0xffff0000, v210
	v_lshlrev_b32_e32 v222, 16, v211
	v_and_b32_e32 v223, 0xffff0000, v211
	v_pk_add_f32 v[90:91], v[146:147], v[90:91]
	v_pk_add_f32 v[222:223], v[148:149], v[222:223]
	v_cvt_pk_bf16_f32 v92, v90, v91
	v_cvt_pk_bf16_f32 v93, v222, v223
	v_lshlrev_b32_e32 v90, 16, v212
	v_and_b32_e32 v91, 0xffff0000, v212
	v_lshlrev_b32_e32 v222, 16, v213
	v_and_b32_e32 v223, 0xffff0000, v213
	v_pk_add_f32 v[90:91], v[150:151], v[90:91]
	v_pk_add_f32 v[222:223], v[152:153], v[222:223]
	v_cvt_pk_bf16_f32 v94, v90, v91
	v_cvt_pk_bf16_f32 v95, v222, v223
	s_nop 1
	v_mfma_f32_32x32x16_bf16 v[2:17], v[38:41], v[92:95], v[2:17]
	global_load_dwordx4 v[38:41], v[176:177], off offset:1024
	global_load_dwordx4 v[146:149], v[72:73], off offset:320
	global_load_dwordx4 v[150:153], v[72:73], off offset:336
	s_waitcnt vmcnt(21) lgkmcnt(1)
	v_lshlrev_b32_e32 v90, 16, v214
	v_and_b32_e32 v91, 0xffff0000, v214
	v_lshlrev_b32_e32 v222, 16, v215
	v_and_b32_e32 v223, 0xffff0000, v215
	v_pk_add_f32 v[90:91], v[154:155], v[90:91]
	v_pk_add_f32 v[222:223], v[156:157], v[222:223]
	v_cvt_pk_bf16_f32 v92, v90, v91
	v_cvt_pk_bf16_f32 v93, v222, v223
	v_lshlrev_b32_e32 v90, 16, v216
	v_and_b32_e32 v91, 0xffff0000, v216
	v_lshlrev_b32_e32 v222, 16, v217
	v_and_b32_e32 v223, 0xffff0000, v217
	v_pk_add_f32 v[90:91], v[158:159], v[90:91]
	v_pk_add_f32 v[222:223], v[160:161], v[222:223]
	v_cvt_pk_bf16_f32 v94, v90, v91
	v_cvt_pk_bf16_f32 v95, v222, v223
	s_nop 1
	v_mfma_f32_32x32x16_bf16 v[2:17], v[42:45], v[92:95], v[2:17]
	global_load_dwordx4 v[42:45], v[176:177], off offset:2048
	global_load_dwordx4 v[154:157], v[72:73], off offset:384
	global_load_dwordx4 v[158:161], v[72:73], off offset:400
	s_waitcnt vmcnt(21) lgkmcnt(0)
	v_lshlrev_b32_e32 v90, 16, v218
	v_and_b32_e32 v91, 0xffff0000, v218
	v_lshlrev_b32_e32 v222, 16, v219
	v_and_b32_e32 v223, 0xffff0000, v219
	v_pk_add_f32 v[90:91], v[166:167], v[90:91]
	v_pk_add_f32 v[222:223], v[168:169], v[222:223]
	v_cvt_pk_bf16_f32 v92, v90, v91
	v_cvt_pk_bf16_f32 v93, v222, v223
	v_lshlrev_b32_e32 v90, 16, v220
	v_and_b32_e32 v91, 0xffff0000, v220
	v_lshlrev_b32_e32 v222, 16, v221
	v_and_b32_e32 v223, 0xffff0000, v221
	v_pk_add_f32 v[90:91], v[170:171], v[90:91]
	v_pk_add_f32 v[222:223], v[172:173], v[222:223]
	v_cvt_pk_bf16_f32 v94, v90, v91
	v_cvt_pk_bf16_f32 v95, v222, v223
	s_nop 1
	v_mfma_f32_32x32x16_bf16 v[2:17], v[46:49], v[92:95], v[2:17]
	global_load_dwordx4 v[46:49], v[176:177], off offset:3072
	global_load_dwordx4 v[166:169], v[72:73], off offset:448
	global_load_dwordx4 v[170:173], v[72:73], off offset:464
	v_lshl_add_u64 v[174:175], v[174:175], 0, s[18:19]
	v_lshl_add_u64 v[176:177], v[176:177], 0, s[18:19]
	s_add_i32 s10, s10, 0x200
	s_and_b32 s10, s10, 0x3fff
	s_add_i32 s2, s2, 1
	s_cmp_lg_u32 s2, 32
	s_cbranch_scc1 .Lcm_loop
	s_waitcnt vmcnt(0)
	s_nop 10
	v_mul_f32_e32 v0, 0x3d372713, v2
	v_mul_f32_e32 v0, v2, v0
	v_fma_f32 v0, v2, v0, v2
	v_mul_f32_e32 v0, 0x3f4c422a, v0
	v_cmp_nlt_f32_e64 s[2:3], |v0|, s39
	s_barrier
	s_and_saveexec_b64 s[10:11], s[2:3]
	s_xor_b64 s[2:3], exec, s[10:11]
	s_cbranch_execz .LBB0_307
	v_add_f32_e64 v18, |v0|, |v0|
	v_mul_f32_e32 v19, 0x3fb8aa3b, v18
	v_rndne_f32_e32 v20, v19
	s_mov_b32 s10, 0x3fb8aa3b
	v_sub_f32_e32 v21, v19, v20
	v_fma_f32 v19, v18, s10, -v19
	v_fmac_f32_e32 v19, 0x32a5705f, v18
	v_add_f32_e32 v19, v21, v19
	v_cvt_i32_f32_e32 v20, v20
	v_exp_f32_e32 v19, v19
	s_mov_b32 s10, 0xc2ce8ed0
	v_cmp_ngt_f32_e32 vcc, s10, v18
	v_ldexp_f32 v19, v19, v20
	s_nop 0
	v_cndmask_b32_e32 v19, 0, v19, vcc
	v_cmp_nlt_f32_e32 vcc, s33, v18
	s_nop 1
	v_cndmask_b32_e32 v18, v235, v19, vcc
	v_add_f32_e32 v18, 1.0, v18
	v_rcp_f32_e32 v18, v18
	s_nop 0
	v_fma_f32 v18, v18, -2.0, 1.0
